# code placement: 64-byte alignment of the hot loop heads (attention, GEMM k-loops, PEER token loops)
# baseline (speedup 1.0000x reference)
.LBB0_35:
	s_add_u32 s6, s6, 0x80
	s_addc_u32 s7, s7, 0
	s_cmpk_lg_i32 s6, 0x800
	s_mov_b32 s15, s16
	s_waitcnt lgkmcnt(0)
	s_barrier
	s_cbranch_scc0 .LBB0_40
	.p2align	6

.LBB0_102:
	s_add_u32 s4, s4, 0x80
	s_addc_u32 s5, s5, 0
	s_cmpk_lg_i32 s4, 0x800
	s_mov_b32 s10, s12
	s_waitcnt lgkmcnt(0)
	s_barrier
	s_cbranch_scc0 .LBB0_107
	.p2align	6

.LBB0_345:
	v_lshlrev_b32_e32 v101, 3, v37
	v_mov_b32_e32 v33, 0
	s_andn2_b64 vcc, exec, s[0:1]
	v_mov_b32_e32 v32, 0
	v_mov_b32_e32 v31, 0
	v_mov_b32_e32 v30, 0
	v_mov_b32_e32 v29, 0
	v_mov_b32_e32 v28, 0
	v_mov_b32_e32 v27, 0
	v_mov_b32_e32 v26, 0
	v_mov_b32_e32 v25, 0
	v_mov_b32_e32 v24, 0
	v_mov_b32_e32 v23, 0
	v_mov_b32_e32 v22, 0
	v_mov_b32_e32 v21, 0
	v_mov_b32_e32 v20, 0
	v_mov_b32_e32 v19, 0
	v_mov_b32_e32 v18, 0
	v_mov_b32_e32 v17, 0
	v_mov_b32_e32 v16, 0
	v_mov_b32_e32 v15, 0
	v_mov_b32_e32 v14, 0
	v_mov_b32_e32 v13, 0
	v_mov_b32_e32 v12, 0
	v_mov_b32_e32 v11, 0
	v_mov_b32_e32 v10, 0
	v_mov_b32_e32 v9, 0
	v_mov_b32_e32 v8, 0
	v_mov_b32_e32 v7, 0
	v_mov_b32_e32 v6, 0
	v_mov_b32_e32 v5, 0
	v_mov_b32_e32 v4, 0
	v_mov_b32_e32 v3, 0
	v_mov_b32_e32 v2, 0
	v_mov_b32_e32 v36, 0
	s_cbranch_vccnz .LBB0_422
	v_ashrrev_i32_e32 v2, 6, v38
	v_add_u32_e32 v4, -4, v2
	v_and_b32_e32 v3, 63, v34
	v_min_u32_e32 v4, 56, v4
	v_cmp_lt_i32_e32 vcc, 3, v2
	v_writelane_b32 v255, s4, 15
	v_and_b32_e32 v6, 64, v219
	v_cndmask_b32_e32 v113, 0, v4, vcc
	v_subrev_co_u32_e32 v4, vcc, 8, v3
	v_writelane_b32 v255, s11, 16
	v_min_u32_e32 v4, 48, v4
	v_xor_b32_e32 v109, 32, v219
	v_add_u32_e32 v111, 64, v6
	v_writelane_b32 v255, s10, 17
	v_cndmask_b32_e64 v4, v4, 0, vcc
	v_lshlrev_b32_e32 v5, 2, v37
	v_cmp_lt_i32_e32 vcc, v109, v111
	v_writelane_b32 v255, s40, 18
	v_cmp_ge_u32_e64 s[0:1], v5, v4
	v_cndmask_b32_e32 v6, v219, v109, vcc
	v_lshlrev_b32_e32 v115, 2, v6
	v_writelane_b32 v255, s0, 19
	v_or_b32_e32 v6, 1, v5
	v_add_u32_e32 v34, 16, v4
	v_writelane_b32 v255, s1, 20
	v_cmp_ge_u32_e64 s[0:1], v6, v4
	v_or_b32_e32 v6, 2, v5
	s_add_i32 s56, s56, 5
	v_writelane_b32 v255, s0, 21
	v_readlane_b32 s3, v254, 31
	v_mul_lo_u32 v2, v2, 31
	v_writelane_b32 v255, s1, 22
	v_cmp_ge_u32_e64 s[0:1], v6, v4
	v_or_b32_e32 v6, 3, v5
	v_mov_b32_e32 v16, v1
	v_writelane_b32 v255, s0, 23
	v_mov_b32_e32 v17, v1
	v_or_b32_e32 v35, 50, v5
	v_writelane_b32 v255, s1, 24
	v_cmp_ge_u32_e64 s[0:1], v6, v4
	v_or_b32_e32 v6, 8, v5
	v_or_b32_e32 v36, 51, v5
	v_writelane_b32 v255, s0, 25
	v_or_b32_e32 v37, 56, v5
	v_or_b32_e32 v38, 57, v5
	v_writelane_b32 v255, s1, 26
	v_cmp_ge_u32_e64 s[0:1], v6, v4
	v_or_b32_e32 v6, 9, v5
	v_or_b32_e32 v39, 58, v5
	v_writelane_b32 v255, s0, 27
	v_or_b32_e32 v40, 59, v5
	v_mov_b32_e32 v7, v1
	v_writelane_b32 v255, s1, 28
	v_cmp_ge_u32_e64 s[0:1], v6, v4
	v_or_b32_e32 v6, 10, v5
	v_mov_b32_e32 v8, v1
	v_writelane_b32 v255, s0, 29
	v_mov_b32_e32 v9, v1
	v_mov_b32_e32 v10, v1
	v_writelane_b32 v255, s1, 30
	v_cmp_ge_u32_e64 s[0:1], v6, v4
	v_or_b32_e32 v6, 11, v5
	v_mov_b32_e32 v11, v1
	v_writelane_b32 v255, s0, 31
	v_mov_b32_e32 v12, v1
	v_mov_b32_e32 v13, v1
	v_writelane_b32 v255, s1, 32
	v_cmp_ge_u32_e64 s[0:1], v6, v4
	v_or_b32_e32 v6, 16, v5
	v_mov_b32_e32 v14, v1
	v_writelane_b32 v255, s0, 33
	v_mov_b32_e32 v15, v1
	s_mov_b32 s66, 0
	v_writelane_b32 v255, s1, 34
	v_cmp_ge_u32_e64 s[0:1], v6, v4
	v_or_b32_e32 v6, 17, v5
	v_add_u32_e32 v114, 8, v113
	v_writelane_b32 v255, s0, 35
	v_mov_b32_e32 v118, 0xf149f2ca
	v_mov_b32_e32 v117, 0
	v_writelane_b32 v255, s1, 36
	v_cmp_lt_u32_e64 s[0:1], v5, v4
	v_cmp_lt_u32_e64 s[30:31], v35, v34
	v_cmp_lt_u32_e64 s[34:35], v36, v34
	v_writelane_b32 v255, s0, 37
	v_cmp_lt_u32_e64 s[36:37], v37, v34
	v_cmp_lt_u32_e64 s[38:39], v38, v34
	v_writelane_b32 v255, s1, 38
	v_cmp_ge_u32_e64 s[0:1], v6, v4
	s_nop 1
	v_writelane_b32 v255, s0, 39
	s_nop 1
	v_writelane_b32 v255, s1, 40
	v_cmp_lt_u32_e64 s[0:1], v6, v34
	v_or_b32_e32 v6, 18, v5
	s_nop 0
	v_writelane_b32 v255, s0, 41
	s_nop 1
	v_writelane_b32 v255, s1, 42
	v_cmp_ge_u32_e64 s[0:1], v6, v4
	s_nop 1
	v_writelane_b32 v255, s0, 43
	s_nop 1
	v_writelane_b32 v255, s1, 44
	v_cmp_lt_u32_e64 s[0:1], v6, v34
	v_or_b32_e32 v6, 19, v5
	s_nop 0
	v_writelane_b32 v255, s0, 45
	s_nop 1
	v_writelane_b32 v255, s1, 46
	v_cmp_ge_u32_e64 s[0:1], v6, v4
	s_nop 1
	v_writelane_b32 v255, s0, 47
	s_nop 1
	v_writelane_b32 v255, s1, 48
	v_cmp_lt_u32_e64 s[0:1], v6, v34
	v_or_b32_e32 v6, 24, v5
	v_cmp_lt_u32_e64 s[74:75], v6, v34
	v_writelane_b32 v255, s0, 49
	s_nop 1
	v_writelane_b32 v255, s1, 50
	v_cmp_ge_u32_e64 s[0:1], v6, v4
	v_or_b32_e32 v6, 25, v5
	v_cmp_ge_u32_e64 s[76:77], v6, v4
	v_writelane_b32 v255, s0, 51
	v_cmp_lt_u32_e64 s[78:79], v6, v34
	v_or_b32_e32 v6, 26, v5
	v_writelane_b32 v255, s1, 52
	s_lshl_b32 s0, s2, 7
	v_cmp_ge_u32_e64 s[80:81], v6, v4
	v_cmp_lt_u32_e64 s[82:83], v6, v34
	v_or_b32_e32 v6, 27, v5
	s_add_u32 s0, s0, s28
	v_cmp_ge_u32_e64 s[84:85], v6, v4
	v_cmp_lt_u32_e64 s[86:87], v6, v34
	v_or_b32_e32 v6, 32, v5
	s_addc_u32 s1, 0, 0
	v_cmp_ge_u32_e64 s[88:89], v6, v4
	v_cmp_lt_u32_e64 s[90:91], v6, v34
	v_or_b32_e32 v6, 33, v5
	s_add_u32 s46, s3, s0
	v_readlane_b32 s0, v254, 32
	v_cmp_ge_u32_e64 s[92:93], v6, v4
	v_cmp_lt_u32_e64 s[50:51], v6, v34
	v_or_b32_e32 v6, 34, v5
	s_addc_u32 s47, s0, s1
	s_lshl_b32 s0, s2, 13
	v_cmp_ge_u32_e64 s[72:73], v6, v4
	v_cmp_lt_u32_e64 s[4:5], v6, v34
	v_or_b32_e32 v6, 35, v5
	s_add_u32 s0, s0, s28
	v_cmp_ge_u32_e64 s[6:7], v6, v4
	v_cmp_lt_u32_e64 s[8:9], v6, v34
	v_or_b32_e32 v6, 40, v5
	s_addc_u32 s1, 0, 0
	v_readlane_b32 s3, v254, 33
	v_cmp_ge_u32_e64 s[10:11], v6, v4
	v_cmp_lt_u32_e64 s[12:13], v6, v34
	v_or_b32_e32 v6, 41, v5
	s_add_u32 s48, s3, s0
	v_readlane_b32 s0, v254, 34
	v_cmp_ge_u32_e64 s[14:15], v6, v4
	v_cmp_lt_u32_e64 s[16:17], v6, v34
	v_or_b32_e32 v6, 42, v5
	s_addc_u32 s49, s0, s1
	s_mul_i32 s0, s2, 31
	v_cmp_ge_u32_e64 s[18:19], v6, v4
	v_cmp_lt_u32_e64 s[20:21], v6, v34
	v_or_b32_e32 v6, 43, v5
	s_addk_i32 s0, 0x6c
	v_cmp_ge_u32_e64 s[22:23], v6, v4
	v_cmp_lt_u32_e64 s[24:25], v6, v34
	v_or_b32_e32 v4, 48, v5
	v_add_u32_e32 v6, s0, v5
	v_cmp_lt_u32_e64 s[26:27], v4, v34
	v_or_b32_e32 v4, 49, v5
	v_sub_u32_e32 v3, v6, v3
	v_cmp_lt_u32_e64 s[28:29], v4, v34
	v_sub_u32_e32 v116, v3, v2
	v_mov_b32_e32 v2, v1
	v_mov_b32_e32 v3, v1
	v_mov_b32_e32 v4, v1
	v_mov_b32_e32 v5, v1
	v_mov_b32_e32 v6, v1
	v_mov_b64_e32 v[32:33], v[16:17]
	s_add_i32 s61, s2, -4
	v_mov_b64_e32 v[30:31], v[14:15]
	v_mov_b64_e32 v[28:29], v[12:13]
	v_mov_b64_e32 v[26:27], v[10:11]
	v_mov_b64_e32 v[24:25], v[8:9]
	v_mov_b64_e32 v[22:23], v[6:7]
	v_mov_b64_e32 v[20:21], v[4:5]
	v_mov_b64_e32 v[18:19], v[2:3]
	v_cmp_lt_u32_e64 s[0:1], v39, v34
	v_cmp_lt_u32_e64 s[2:3], v40, v34
	.p2align	6

.LBB0_426:
	s_bitcmp1_b32 s17, 0
	s_cselect_b32 s4, 0x4800, 0
	v_or_b32_e32 v0, s4, v172
	v_lshl_add_u32 v3, v173, 1, v0
	v_lshl_add_u32 v0, v177, 1, v0
	s_waitcnt vmcnt(3)
	ds_write_b128 v3, v[128:131]
	s_waitcnt vmcnt(2)
	ds_write_b128 v3, v[132:135] offset:9216
	s_waitcnt vmcnt(1)
	ds_write_b128 v0, v[136:139]
	s_waitcnt vmcnt(0)
	ds_write_b128 v0, v[140:143] offset:9216
	.p2align	6

.LBB0_446:
	s_add_u32 s6, s6, 0x80
	s_addc_u32 s7, s7, 0
	s_cmpk_lg_i32 s6, 0x800
	s_mov_b32 s11, s13
	s_waitcnt lgkmcnt(0)
	s_barrier
	s_cbranch_scc0 .LBB0_451
	.p2align	6

.LBB0_537:
	s_or_b64 exec, exec, s[18:19]
	s_and_b64 s[0:1], exec, s[16:17]
	s_or_b64 s[6:7], s[0:1], s[6:7]
	s_andn2_b64 exec, exec, s[6:7]
	s_cbranch_execz .LBB0_555
	.p2align	6

.LBB0_557:
	s_or_b64 exec, exec, s[18:19]
	s_and_b64 s[6:7], exec, s[16:17]
	s_or_b64 s[0:1], s[6:7], s[0:1]
	s_andn2_b64 exec, exec, s[0:1]
	s_cbranch_execz .LBB0_534
	.p2align	6
